# all K-loop MFMA groups reordered into adjacent accumulate pairs (dependency-preserving), incl. the register-renamed groups of the FFN-up loop
# speedup vs baseline: 1.0191x; 1.0098x over previous
; #define PG8_STAGE(bufoff, gbase, voff) do { _Pragma("unroll") for (int _i = 0; _i < 2; ++_i) \
;         __builtin_amdgcn_global_load_lds((const unsigned*)((const char*)(gbase) + (voff)[_i]), (PG8_LAS unsigned*)(lds + (bufoff) + ldsw + _i * 8192), 16, 0, 0); } while (0)
; #define PG8_LDA(dst, b, h) do { _Pragma("unroll") for (int m = 0; m < 4; ++m) _Pragma("unroll") for (int k = 0; k < 2; ++k) dst[m][k] = *(const PG8_LAS bf16x8*)(lds + PG8_SA(b, h) + aoff + m * 2048 + k * 1024); } while (0)
; #define PG8_LDB(dst, b, h) do { _Pragma("unroll") for (int n = 0; n < 2; ++n) _Pragma("unroll") for (int k = 0; k < 2; ++k) dst[n][k] = *(const PG8_LAS bf16x8*)(lds + PG8_SB(b, h) + boff + n * 2048 + k * 1024); } while (0)
; #define PG8_MMA(ai, bj, At, Bt) do { __builtin_amdgcn_s_setprio(1); _Pragma("unroll") for (int m = 0; m < 4; ++m) _Pragma("unroll") for (int n = 0; n < 2; ++n) _Pragma("unroll") for (int k = 0; k < 2; ++k) \
;         acc[ai][bj][m][n] = __builtin_amdgcn_mfma_f32_16x16x32_bf16(Bt[n][k], At[m][k], acc[ai][bj][m][n], 0, 0, 0); __builtin_amdgcn_s_setprio(0); } while (0)
; #define PG8_WAIT_V(n) asm volatile("s_waitcnt vmcnt(" #n ")" ::: "memory")
; #define PG8_WAIT_L(n) asm volatile("s_waitcnt lgkmcnt(" #n ")" ::: "memory")
; #define PG8_BAR __builtin_amdgcn_s_barrier()
; template <class Epi, class Sched, bool ALIGN_EPI = false, bool SP2 = false>
; __device__ __forceinline__ void gemm_phase(PG8_LAS unsigned char* lds, const Gemm g, const Sched& S, const Epi& E) {
;     ...
;             const char* a1 = cA + (size_t)(t + 1) * kstep;
;             const char* a2 = last ? nA : cA + (size_t)(t + 2) * kstep; const char* b2 = last ? nB : cB + (size_t)(t + 2) * kstep;
;             const char* a3 = a2 + kstep; const char* b3 = b2 + kstep;
;             if (last && has_next) S.a_ready(nxt);
;             if constexpr (SP2) {
;             PG8_LDB(B0, 0, 0); PG8_LDB(B1, 0, 1); PG8_SCHED; PG8_LDA(At, 0, 0); PG8_STAGE(PG8_SA(1, 1), a1 + hstep, voffA);
;             PG8_WAIT_V(8); PG8_WAIT_L(0); PG8_BAR; PG8_MMA(0, 0, At, B0); PG8_MMA(0, 1, At, B1); PG8_BAR; PG8_SCHED;
;             PG8_LDA(At, 0, 1); PG8_STAGE(PG8_SB(0, 0), b2, voffB); PG8_STAGE(PG8_SB(0, 1), b2 + hstep, voffB); PG8_STAGE(PG8_SA(0, 0), a2, voffA);
;             PG8_WAIT_V(8); PG8_WAIT_L(0); PG8_BAR; PG8_MMA(1, 0, At, B0); PG8_MMA(1, 1, At, B1); PG8_BAR; PG8_SCHED;
.LBB0_2487:
	v_add_u32_e32 v3, s67, v183
	s_add_i32 s81, s50, 2
	ds_read_b128 v[154:157], v3
	ds_read_b128 v[158:161], v3 offset:1024
	ds_read_b128 v[162:165], v3 offset:2048
	ds_read_b128 v[166:169], v3 offset:3072
	v_add_u32_e32 v3, s68, v183
	s_add_u32 s51, s42, s46
	ds_read_b128 v[170:173], v3
	ds_read_b128 v[174:177], v3 offset:1024
	ds_read_b128 v[178:181], v3 offset:2048
	ds_read_b128 v[184:187], v3 offset:3072
	s_addc_u32 s52, s43, s47
	s_add_u32 s51, s51, 0x100
	s_addc_u32 s52, s52, 0
	s_add_u32 s82, s79, s46
	s_addc_u32 s83, s80, s47
	s_cmp_eq_u32 s9, s50
	s_cselect_b32 s53, s27, s52
	s_cselect_b32 s52, s35, s51
	s_cselect_b32 s51, s31, s83
	s_cselect_b32 s50, s78, s82
	v_lshl_add_u64 v[4:5], v[150:151], 0, s[46:47]
	s_add_i32 m0, s11, 0xc000
	ds_read_b128 v[188:191], v211
	ds_read_b128 v[192:195], v211 offset:1024
	ds_read_b128 v[196:199], v211 offset:2048
	ds_read_b128 v[200:203], v211 offset:3072
	ds_read_b128 v[204:207], v211 offset:4096
	ds_read_b128 v[212:215], v211 offset:5120
	ds_read_b128 v[216:219], v211 offset:6144
	ds_read_b128 v[220:223], v211 offset:7168
	global_load_lds_dwordx4 v[4:5], off
	v_lshl_add_u64 v[4:5], v[152:153], 0, s[46:47]
	s_add_i32 m0, s11, 0xe000
	s_nop 0
	global_load_lds_dwordx4 v[4:5], off
	s_waitcnt vmcnt(8)
	s_waitcnt lgkmcnt(0)
	s_barrier
	s_setprio 1
	s_waitcnt lgkmcnt(0)
	v_mfma_f32_16x16x32_bf16 v[130:133], v[154:157], v[188:191], v[130:133]
	v_mfma_f32_16x16x32_bf16 v[130:133], v[158:161], v[192:195], v[130:133]
	v_mfma_f32_16x16x32_bf16 v[126:129], v[162:165], v[188:191], v[126:129]
	v_mfma_f32_16x16x32_bf16 v[126:129], v[166:169], v[192:195], v[126:129]
	v_mfma_f32_16x16x32_bf16 v[114:117], v[154:157], v[196:199], v[114:117]
	v_mfma_f32_16x16x32_bf16 v[114:117], v[158:161], v[200:203], v[114:117]
	v_mfma_f32_16x16x32_bf16 v[110:113], v[162:165], v[196:199], v[110:113]
	v_mfma_f32_16x16x32_bf16 v[110:113], v[166:169], v[200:203], v[110:113]
	v_mfma_f32_16x16x32_bf16 v[98:101], v[154:157], v[204:207], v[98:101]
	v_mfma_f32_16x16x32_bf16 v[98:101], v[158:161], v[212:215], v[98:101]
	v_mfma_f32_16x16x32_bf16 v[94:97], v[162:165], v[204:207], v[94:97]
	v_mfma_f32_16x16x32_bf16 v[94:97], v[166:169], v[212:215], v[94:97]
	v_mfma_f32_16x16x32_bf16 v[82:85], v[154:157], v[216:219], v[82:85]
	v_mfma_f32_16x16x32_bf16 v[82:85], v[158:161], v[220:223], v[82:85]
	v_mfma_f32_16x16x32_bf16 v[78:81], v[162:165], v[216:219], v[78:81]
	v_mfma_f32_16x16x32_bf16 v[78:81], v[166:169], v[220:223], v[78:81]
	s_setprio 0
	s_setprio 1
	v_mfma_f32_16x16x32_bf16 v[122:125], v[170:173], v[188:191], v[122:125]
	v_mfma_f32_16x16x32_bf16 v[122:125], v[174:177], v[192:195], v[122:125]
	v_mfma_f32_16x16x32_bf16 v[118:121], v[178:181], v[188:191], v[118:121]
	v_mfma_f32_16x16x32_bf16 v[118:121], v[184:187], v[192:195], v[118:121]
	v_mfma_f32_16x16x32_bf16 v[106:109], v[170:173], v[196:199], v[106:109]
	v_mfma_f32_16x16x32_bf16 v[106:109], v[174:177], v[200:203], v[106:109]
	v_mfma_f32_16x16x32_bf16 v[102:105], v[178:181], v[196:199], v[102:105]
	v_mfma_f32_16x16x32_bf16 v[102:105], v[184:187], v[200:203], v[102:105]
	v_mfma_f32_16x16x32_bf16 v[90:93], v[170:173], v[204:207], v[90:93]
	v_mfma_f32_16x16x32_bf16 v[90:93], v[174:177], v[212:215], v[90:93]
	v_mfma_f32_16x16x32_bf16 v[86:89], v[178:181], v[204:207], v[86:89]
	v_mfma_f32_16x16x32_bf16 v[86:89], v[184:187], v[212:215], v[86:89]
	v_mfma_f32_16x16x32_bf16 v[74:77], v[170:173], v[216:219], v[74:77]
	v_mfma_f32_16x16x32_bf16 v[74:77], v[174:177], v[220:223], v[74:77]
	v_mfma_f32_16x16x32_bf16 v[70:73], v[178:181], v[216:219], v[70:73]
	v_mfma_f32_16x16x32_bf16 v[70:73], v[184:187], v[220:223], v[70:73]
	s_setprio 0
	s_barrier
	s_add_i32 s82, s67, s55
	s_mov_b32 m0, s82
	ds_read_b128 v[188:191], v211 offset:16384
	ds_read_b128 v[192:195], v211 offset:17408
	ds_read_b128 v[196:199], v211 offset:18432
	ds_read_b128 v[200:203], v211 offset:19456
	ds_read_b128 v[204:207], v211 offset:20480
	ds_read_b128 v[212:215], v211 offset:21504
	ds_read_b128 v[216:219], v211 offset:22528
	ds_read_b128 v[220:223], v211 offset:23552
	global_load_lds_dwordx4 v134, s[50:51]
	s_add_i32 m0, s82, 0x2000
	s_add_u32 s82, s50, 0x100000
	s_addc_u32 s83, s51, 0
	s_add_i32 s84, s68, s55
	global_load_lds_dwordx4 v136, s[50:51]
	s_mov_b32 m0, s84
	s_nop 0
	global_load_lds_dwordx4 v134, s[82:83]
	s_add_i32 m0, s84, 0x2000
	s_nop 0
	global_load_lds_dwordx4 v136, s[82:83]
	s_mov_b32 m0, s11
	s_nop 0
	global_load_lds_dwordx4 v134, s[52:53]
	s_mov_b32 m0, s57
	s_nop 0
	global_load_lds_dwordx4 v136, s[52:53]
	s_waitcnt vmcnt(8)
	s_waitcnt lgkmcnt(0)
	s_barrier
; #define PG8_STAGE(bufoff, gbase, voff) do { _Pragma("unroll") for (int _i = 0; _i < 2; ++_i) \
;         __builtin_amdgcn_global_load_lds((const unsigned*)((const char*)(gbase) + (voff)[_i]), (PG8_LAS unsigned*)(lds + (bufoff) + ldsw + _i * 8192), 16, 0, 0); } while (0)
; #define PG8_LDA(dst, b, h) do { _Pragma("unroll") for (int m = 0; m < 4; ++m) _Pragma("unroll") for (int k = 0; k < 2; ++k) dst[m][k] = *(const PG8_LAS bf16x8*)(lds + PG8_SA(b, h) + aoff + m * 2048 + k * 1024); } while (0)
; #define PG8_LDB(dst, b, h) do { _Pragma("unroll") for (int n = 0; n < 2; ++n) _Pragma("unroll") for (int k = 0; k < 2; ++k) dst[n][k] = *(const PG8_LAS bf16x8*)(lds + PG8_SB(b, h) + boff + n * 2048 + k * 1024); } while (0)
; #define PG8_MMA(ai, bj, At, Bt) do { __builtin_amdgcn_s_setprio(1); _Pragma("unroll") for (int m = 0; m < 4; ++m) _Pragma("unroll") for (int n = 0; n < 2; ++n) _Pragma("unroll") for (int k = 0; k < 2; ++k) \
;         acc[ai][bj][m][n] = __builtin_amdgcn_mfma_f32_16x16x32_bf16(Bt[n][k], At[m][k], acc[ai][bj][m][n], 0, 0, 0); __builtin_amdgcn_s_setprio(0); } while (0)
; #define PG8_WAIT_V(n) asm volatile("s_waitcnt vmcnt(" #n ")" ::: "memory")
; #define PG8_WAIT_L(n) asm volatile("s_waitcnt lgkmcnt(" #n ")" ::: "memory")
; #define PG8_BAR __builtin_amdgcn_s_barrier()
; #define PG8_SCHED __builtin_amdgcn_sched_barrier(0)
; template <class Epi, class Sched, bool ALIGN_EPI = false, bool SP2 = false>
; __device__ __forceinline__ void gemm_phase(PG8_LAS unsigned char* lds, const Gemm g, const Sched& S, const Epi& E) {
;     ...
;             PG8_WAIT_V(8); PG8_WAIT_L(0); PG8_BAR; PG8_MMA(1, 0, At, B0); PG8_MMA(1, 1, At, B1); PG8_BAR; PG8_SCHED;
;             PG8_LDB(B0, 1, 0); PG8_LDB(B1, 1, 1); PG8_SCHED; PG8_LDA(At, 1, 0); PG8_STAGE(PG8_SA(0, 1), a2 + hstep, voffA);
;             PG8_WAIT_V(8); PG8_WAIT_L(0); PG8_BAR; PG8_MMA(0, 0, At, B0); PG8_MMA(0, 1, At, B1); PG8_BAR; PG8_SCHED;
	s_setprio 1
	s_waitcnt lgkmcnt(0)
	v_mfma_f32_16x16x32_bf16 v[66:69], v[154:157], v[188:191], v[66:69]
	v_mfma_f32_16x16x32_bf16 v[66:69], v[158:161], v[192:195], v[66:69]
	v_mfma_f32_16x16x32_bf16 v[62:65], v[162:165], v[188:191], v[62:65]
	v_mfma_f32_16x16x32_bf16 v[62:65], v[166:169], v[192:195], v[62:65]
	v_mfma_f32_16x16x32_bf16 v[50:53], v[154:157], v[196:199], v[50:53]
	v_mfma_f32_16x16x32_bf16 v[50:53], v[158:161], v[200:203], v[50:53]
	v_mfma_f32_16x16x32_bf16 v[46:49], v[162:165], v[196:199], v[46:49]
	v_mfma_f32_16x16x32_bf16 v[46:49], v[166:169], v[200:203], v[46:49]
	v_mfma_f32_16x16x32_bf16 v[34:37], v[154:157], v[204:207], v[34:37]
	v_mfma_f32_16x16x32_bf16 v[34:37], v[158:161], v[212:215], v[34:37]
	v_mfma_f32_16x16x32_bf16 v[30:33], v[162:165], v[204:207], v[30:33]
	v_mfma_f32_16x16x32_bf16 v[30:33], v[166:169], v[212:215], v[30:33]
	v_mfma_f32_16x16x32_bf16 v[18:21], v[154:157], v[216:219], v[18:21]
	v_mfma_f32_16x16x32_bf16 v[18:21], v[158:161], v[220:223], v[18:21]
	v_mfma_f32_16x16x32_bf16 v[14:17], v[162:165], v[216:219], v[14:17]
	v_mfma_f32_16x16x32_bf16 v[14:17], v[166:169], v[220:223], v[14:17]
	s_setprio 0
	s_setprio 1
	v_mfma_f32_16x16x32_bf16 v[58:61], v[170:173], v[188:191], v[58:61]
	v_mfma_f32_16x16x32_bf16 v[58:61], v[174:177], v[192:195], v[58:61]
	v_mfma_f32_16x16x32_bf16 v[54:57], v[178:181], v[188:191], v[54:57]
	v_mfma_f32_16x16x32_bf16 v[54:57], v[184:187], v[192:195], v[54:57]
	v_mfma_f32_16x16x32_bf16 v[42:45], v[170:173], v[196:199], v[42:45]
	v_mfma_f32_16x16x32_bf16 v[42:45], v[174:177], v[200:203], v[42:45]
	v_mfma_f32_16x16x32_bf16 v[38:41], v[178:181], v[196:199], v[38:41]
	v_mfma_f32_16x16x32_bf16 v[38:41], v[184:187], v[200:203], v[38:41]
	v_mfma_f32_16x16x32_bf16 v[26:29], v[170:173], v[204:207], v[26:29]
	v_mfma_f32_16x16x32_bf16 v[26:29], v[174:177], v[212:215], v[26:29]
	v_mfma_f32_16x16x32_bf16 v[22:25], v[178:181], v[204:207], v[22:25]
	v_mfma_f32_16x16x32_bf16 v[22:25], v[184:187], v[212:215], v[22:25]
	v_mfma_f32_16x16x32_bf16 v[10:13], v[170:173], v[216:219], v[10:13]
	v_mfma_f32_16x16x32_bf16 v[10:13], v[174:177], v[220:223], v[10:13]
	v_mfma_f32_16x16x32_bf16 v[4:7], v[178:181], v[216:219], v[6:9]
	v_mfma_f32_16x16x32_bf16 v[4:7], v[184:187], v[220:223], v[4:7]
	s_setprio 0
	s_barrier
	s_add_i32 s82, 0, 0x18000
	v_add_u32_e32 v3, s82, v183
	s_add_i32 s83, 0, 0x1c000
	ds_read_b128 v[154:157], v3
	ds_read_b128 v[158:161], v3 offset:1024
	ds_read_b128 v[162:165], v3 offset:2048
	ds_read_b128 v[166:169], v3 offset:3072
	v_add_u32_e32 v3, s83, v183
	ds_read_b128 v[170:173], v3
	ds_read_b128 v[174:177], v3 offset:1024
	ds_read_b128 v[178:181], v3 offset:2048
	ds_read_b128 v[184:187], v3 offset:3072
	s_add_u32 s52, s52, 0x100000
	s_addc_u32 s53, s53, 0
	s_mov_b32 m0, s60
	ds_read_b128 v[188:191], v211 offset:32768
	ds_read_b128 v[192:195], v211 offset:33792
	ds_read_b128 v[196:199], v211 offset:34816
	ds_read_b128 v[200:203], v211 offset:35840
	ds_read_b128 v[204:207], v211 offset:36864
	ds_read_b128 v[212:215], v211 offset:37888
	ds_read_b128 v[216:219], v211 offset:38912
	ds_read_b128 v[220:223], v211 offset:39936
	global_load_lds_dwordx4 v134, s[52:53]
	s_mov_b32 m0, s61
	s_nop 0
	global_load_lds_dwordx4 v136, s[52:53]
	s_waitcnt vmcnt(8)
	s_waitcnt lgkmcnt(0)
	s_barrier
	s_setprio 1
	s_waitcnt lgkmcnt(0)
	v_mfma_f32_16x16x32_bf16 v[130:133], v[154:157], v[188:191], v[130:133]
	v_mfma_f32_16x16x32_bf16 v[130:133], v[158:161], v[192:195], v[130:133]
	v_mfma_f32_16x16x32_bf16 v[126:129], v[162:165], v[188:191], v[126:129]
	v_mfma_f32_16x16x32_bf16 v[126:129], v[166:169], v[192:195], v[126:129]
	v_mfma_f32_16x16x32_bf16 v[114:117], v[154:157], v[196:199], v[114:117]
	v_mfma_f32_16x16x32_bf16 v[114:117], v[158:161], v[200:203], v[114:117]
	v_mfma_f32_16x16x32_bf16 v[110:113], v[162:165], v[196:199], v[110:113]
	v_mfma_f32_16x16x32_bf16 v[110:113], v[166:169], v[200:203], v[110:113]
	v_mfma_f32_16x16x32_bf16 v[98:101], v[154:157], v[204:207], v[98:101]
	v_mfma_f32_16x16x32_bf16 v[98:101], v[158:161], v[212:215], v[98:101]
	v_mfma_f32_16x16x32_bf16 v[94:97], v[162:165], v[204:207], v[94:97]
	v_mfma_f32_16x16x32_bf16 v[94:97], v[166:169], v[212:215], v[94:97]
	v_mfma_f32_16x16x32_bf16 v[82:85], v[154:157], v[216:219], v[82:85]
	v_mfma_f32_16x16x32_bf16 v[82:85], v[158:161], v[220:223], v[82:85]
	v_mfma_f32_16x16x32_bf16 v[78:81], v[162:165], v[216:219], v[78:81]
	v_mfma_f32_16x16x32_bf16 v[78:81], v[166:169], v[220:223], v[78:81]
	s_setprio 0
	s_setprio 1
	v_mfma_f32_16x16x32_bf16 v[122:125], v[170:173], v[188:191], v[122:125]
	v_mfma_f32_16x16x32_bf16 v[122:125], v[174:177], v[192:195], v[122:125]
	v_mfma_f32_16x16x32_bf16 v[118:121], v[178:181], v[188:191], v[118:121]
	v_mfma_f32_16x16x32_bf16 v[118:121], v[184:187], v[192:195], v[118:121]
	v_mfma_f32_16x16x32_bf16 v[106:109], v[170:173], v[196:199], v[106:109]
	v_mfma_f32_16x16x32_bf16 v[106:109], v[174:177], v[200:203], v[106:109]
	v_mfma_f32_16x16x32_bf16 v[102:105], v[178:181], v[196:199], v[102:105]
	v_mfma_f32_16x16x32_bf16 v[102:105], v[184:187], v[200:203], v[102:105]
	v_mfma_f32_16x16x32_bf16 v[90:93], v[170:173], v[204:207], v[90:93]
	v_mfma_f32_16x16x32_bf16 v[90:93], v[174:177], v[212:215], v[90:93]
	v_mfma_f32_16x16x32_bf16 v[86:89], v[178:181], v[204:207], v[86:89]
	v_mfma_f32_16x16x32_bf16 v[86:89], v[184:187], v[212:215], v[86:89]
	v_mfma_f32_16x16x32_bf16 v[74:77], v[170:173], v[216:219], v[74:77]
	v_mfma_f32_16x16x32_bf16 v[74:77], v[174:177], v[220:223], v[74:77]
	v_mfma_f32_16x16x32_bf16 v[70:73], v[178:181], v[216:219], v[70:73]
	v_mfma_f32_16x16x32_bf16 v[70:73], v[184:187], v[220:223], v[70:73]
	s_setprio 0
	s_barrier
; #define PG8_STAGE(bufoff, gbase, voff) do { _Pragma("unroll") for (int _i = 0; _i < 2; ++_i) \
;         __builtin_amdgcn_global_load_lds((const unsigned*)((const char*)(gbase) + (voff)[_i]), (PG8_LAS unsigned*)(lds + (bufoff) + ldsw + _i * 8192), 16, 0, 0); } while (0)
; #define PG8_LDA(dst, b, h) do { _Pragma("unroll") for (int m = 0; m < 4; ++m) _Pragma("unroll") for (int k = 0; k < 2; ++k) dst[m][k] = *(const PG8_LAS bf16x8*)(lds + PG8_SA(b, h) + aoff + m * 2048 + k * 1024); } while (0)
; #define PG8_MMA(ai, bj, At, Bt) do { __builtin_amdgcn_s_setprio(1); _Pragma("unroll") for (int m = 0; m < 4; ++m) _Pragma("unroll") for (int n = 0; n < 2; ++n) _Pragma("unroll") for (int k = 0; k < 2; ++k) \
;         acc[ai][bj][m][n] = __builtin_amdgcn_mfma_f32_16x16x32_bf16(Bt[n][k], At[m][k], acc[ai][bj][m][n], 0, 0, 0); __builtin_amdgcn_s_setprio(0); } while (0)
; #define PG8_WAIT_V(n) asm volatile("s_waitcnt vmcnt(" #n ")" ::: "memory")
; #define PG8_WAIT_L(n) asm volatile("s_waitcnt lgkmcnt(" #n ")" ::: "memory")
; #define PG8_BAR __builtin_amdgcn_s_barrier()
; #define PG8_SCHED __builtin_amdgcn_sched_barrier(0)
; template <class Epi, class Sched, bool ALIGN_EPI = false, bool SP2 = false>
; __device__ __forceinline__ void gemm_phase(PG8_LAS unsigned char* lds, const Gemm g, const Sched& S, const Epi& E) {
;     ...
;             PG8_LDA(At, 1, 1); PG8_STAGE(PG8_SB(1, 0), b3, voffB); PG8_STAGE(PG8_SB(1, 1), b3 + hstep, voffB); PG8_STAGE(PG8_SA(1, 0), a3, voffA);
;             PG8_WAIT_V(8); PG8_WAIT_L(0); PG8_BAR; PG8_MMA(1, 0, At, B0); PG8_MMA(1, 1, At, B1); PG8_BAR; PG8_SCHED;
	s_add_u32 s100, s52, 0xfff00080
	s_addc_u32 s101, s53, -1
	s_add_u32 s98, s50, 0x80
	s_addc_u32 s99, s51, 0
	s_add_i32 s52, s82, s55
	s_mov_b32 m0, s52
	ds_read_b128 v[188:191], v211 offset:49152
	ds_read_b128 v[192:195], v211 offset:50176
	ds_read_b128 v[196:199], v211 offset:51200
	ds_read_b128 v[200:203], v211 offset:52224
	ds_read_b128 v[204:207], v211 offset:53248
	ds_read_b128 v[212:215], v211 offset:54272
	ds_read_b128 v[216:219], v211 offset:55296
	ds_read_b128 v[220:223], v211 offset:56320
	global_load_lds_dwordx4 v134, s[98:99]
	s_add_i32 m0, s52, 0x2000
	s_add_u32 s50, s50, 0x100080
	s_addc_u32 s51, s51, 0
	s_add_i32 s52, s83, s55
	global_load_lds_dwordx4 v136, s[98:99]
	s_mov_b32 m0, s52
	s_nop 0
	global_load_lds_dwordx4 v134, s[50:51]
	s_add_i32 m0, s52, 0x2000
	s_nop 0
	global_load_lds_dwordx4 v136, s[50:51]
	s_mov_b32 m0, s63
	s_nop 0
	global_load_lds_dwordx4 v134, s[100:101]
	s_mov_b32 m0, s64
	s_nop 0
	global_load_lds_dwordx4 v136, s[100:101]
	s_waitcnt vmcnt(8)
	s_waitcnt lgkmcnt(0)
	s_barrier
	s_setprio 1
	s_waitcnt lgkmcnt(0)
	v_mfma_f32_16x16x32_bf16 v[66:69], v[154:157], v[188:191], v[66:69]
	v_mfma_f32_16x16x32_bf16 v[66:69], v[158:161], v[192:195], v[66:69]
	v_mfma_f32_16x16x32_bf16 v[62:65], v[162:165], v[188:191], v[62:65]
	v_mfma_f32_16x16x32_bf16 v[62:65], v[166:169], v[192:195], v[62:65]
	v_mfma_f32_16x16x32_bf16 v[50:53], v[154:157], v[196:199], v[50:53]
	v_mfma_f32_16x16x32_bf16 v[50:53], v[158:161], v[200:203], v[50:53]
	v_mfma_f32_16x16x32_bf16 v[46:49], v[162:165], v[196:199], v[46:49]
	v_mfma_f32_16x16x32_bf16 v[46:49], v[166:169], v[200:203], v[46:49]
	v_mfma_f32_16x16x32_bf16 v[34:37], v[154:157], v[204:207], v[34:37]
	v_mfma_f32_16x16x32_bf16 v[34:37], v[158:161], v[212:215], v[34:37]
	v_mfma_f32_16x16x32_bf16 v[30:33], v[162:165], v[204:207], v[30:33]
	v_mfma_f32_16x16x32_bf16 v[30:33], v[166:169], v[212:215], v[30:33]
	v_mfma_f32_16x16x32_bf16 v[18:21], v[154:157], v[216:219], v[18:21]
	v_mfma_f32_16x16x32_bf16 v[18:21], v[158:161], v[220:223], v[18:21]
	v_mfma_f32_16x16x32_bf16 v[14:17], v[162:165], v[216:219], v[14:17]
	v_mfma_f32_16x16x32_bf16 v[14:17], v[166:169], v[220:223], v[14:17]
	s_setprio 0
	s_setprio 1
	v_mfma_f32_16x16x32_bf16 v[58:61], v[170:173], v[188:191], v[58:61]
	v_mfma_f32_16x16x32_bf16 v[58:61], v[174:177], v[192:195], v[58:61]
	v_mfma_f32_16x16x32_bf16 v[54:57], v[178:181], v[188:191], v[54:57]
	v_mfma_f32_16x16x32_bf16 v[54:57], v[184:187], v[192:195], v[54:57]
	v_mfma_f32_16x16x32_bf16 v[42:45], v[170:173], v[196:199], v[42:45]
	v_mfma_f32_16x16x32_bf16 v[42:45], v[174:177], v[200:203], v[42:45]
	v_mfma_f32_16x16x32_bf16 v[38:41], v[178:181], v[196:199], v[38:41]
	v_mfma_f32_16x16x32_bf16 v[38:41], v[184:187], v[200:203], v[38:41]
	v_mfma_f32_16x16x32_bf16 v[26:29], v[170:173], v[204:207], v[26:29]
	v_mfma_f32_16x16x32_bf16 v[26:29], v[174:177], v[212:215], v[26:29]
	v_mfma_f32_16x16x32_bf16 v[22:25], v[178:181], v[204:207], v[22:25]
	v_mfma_f32_16x16x32_bf16 v[22:25], v[184:187], v[212:215], v[22:25]
	v_mfma_f32_16x16x32_bf16 v[8:11], v[170:173], v[216:219], v[10:13]
	v_mfma_f32_16x16x32_bf16 v[10:13], v[174:177], v[220:223], v[8:11]
	v_mfma_f32_16x16x32_bf16 v[4:7], v[178:181], v[216:219], v[4:7]
	v_mfma_f32_16x16x32_bf16 v[6:9], v[184:187], v[220:223], v[4:7]
	s_setprio 0
	s_barrier
	s_add_u32 s46, s46, 0x100
	s_addc_u32 s47, s47, 0
	s_cmp_ge_i32 s81, s77
	s_cbranch_scc1 .LBB0_2489
	s_mov_b32 s50, s81
	s_branch .LBB0_2485

; #define PG8_STAGE(bufoff, gbase, voff) do { _Pragma("unroll") for (int _i = 0; _i < 2; ++_i) \
;         __builtin_amdgcn_global_load_lds((const unsigned*)((const char*)(gbase) + (voff)[_i]), (PG8_LAS unsigned*)(lds + (bufoff) + ldsw + _i * 8192), 16, 0, 0); } while (0)
; #define PG8_LDA(dst, b, h) do { _Pragma("unroll") for (int m = 0; m < 4; ++m) _Pragma("unroll") for (int k = 0; k < 2; ++k) dst[m][k] = *(const PG8_LAS bf16x8*)(lds + PG8_SA(b, h) + aoff + m * 2048 + k * 1024); } while (0)
; #define PG8_LDB(dst, b, h) do { _Pragma("unroll") for (int n = 0; n < 2; ++n) _Pragma("unroll") for (int k = 0; k < 2; ++k) dst[n][k] = *(const PG8_LAS bf16x8*)(lds + PG8_SB(b, h) + boff + n * 2048 + k * 1024); } while (0)
; #define PG8_MMA(ai, bj, At, Bt) do { __builtin_amdgcn_s_setprio(1); _Pragma("unroll") for (int m = 0; m < 4; ++m) _Pragma("unroll") for (int n = 0; n < 2; ++n) _Pragma("unroll") for (int k = 0; k < 2; ++k) \
;         acc[ai][bj][m][n] = __builtin_amdgcn_mfma_f32_16x16x32_bf16(Bt[n][k], At[m][k], acc[ai][bj][m][n], 0, 0, 0); __builtin_amdgcn_s_setprio(0); } while (0)
; #define PG8_WAIT_V(n) asm volatile("s_waitcnt vmcnt(" #n ")" ::: "memory")
; #define PG8_WAIT_L(n) asm volatile("s_waitcnt lgkmcnt(" #n ")" ::: "memory")
; #define PG8_BAR __builtin_amdgcn_s_barrier()
; #define PG8_SCHED __builtin_amdgcn_sched_barrier(0)
; template <class Epi, class Sched, bool ALIGN_EPI = false, bool SP2 = false>
; __device__ __forceinline__ void gemm_phase(PG8_LAS unsigned char* lds, const Gemm g, const Sched& S, const Epi& E) {
;     ...
;             const char* a2 = last ? nA : cA + (size_t)(t + 2) * kstep; const char* b2 = last ? nB : cB + (size_t)(t + 2) * kstep;
;             const char* a3 = a2 + kstep; const char* b3 = b2 + kstep;
;             if (last && has_next) S.a_ready(nxt);
;             if constexpr (SP2) {
;             PG8_LDB(B0, 0, 0); PG8_LDB(B1, 0, 1); PG8_SCHED; PG8_LDA(At, 0, 0); PG8_STAGE(PG8_SA(1, 1), a1 + hstep, voffA);
;             PG8_WAIT_V(8); PG8_WAIT_L(0); PG8_BAR; PG8_MMA(0, 0, At, B0); PG8_MMA(0, 1, At, B1); PG8_BAR; PG8_SCHED;
;             PG8_LDA(At, 0, 1); PG8_STAGE(PG8_SB(0, 0), b2, voffB); PG8_STAGE(PG8_SB(0, 1), b2 + hstep, voffB); PG8_STAGE(PG8_SA(0, 0), a2, voffA);
;             PG8_WAIT_V(8); PG8_WAIT_L(0); PG8_BAR; PG8_MMA(1, 0, At, B0); PG8_MMA(1, 1, At, B1); PG8_BAR; PG8_SCHED;
.LBB0_2650:
	ds_read_b128 v[10:13], v195
	ds_read_b128 v[14:17], v195 offset:1024
	ds_read_b128 v[42:45], v195 offset:2048
	ds_read_b128 v[46:49], v195 offset:3072
	ds_read_b128 v[50:53], v238
	ds_read_b128 v[54:57], v238 offset:1024
	ds_read_b128 v[58:61], v238 offset:2048
	ds_read_b128 v[62:65], v238 offset:3072
	s_add_u32 s88, s86, 0xfff00080
	s_addc_u32 s89, s87, -1
	s_cmp_eq_u32 s93, 60
	s_cselect_b32 s91, s19, s89
	s_cselect_b32 s90, s69, s88
	s_cselect_b32 s89, s77, s92
	s_cselect_b32 s88, s79, s85
	s_add_i32 m0, s62, 0xc000
	ds_read_b128 v[66:69], v239
	ds_read_b128 v[70:73], v239 offset:1024
	ds_read_b128 v[170:173], v239 offset:2048
	ds_read_b128 v[174:177], v239 offset:3072
	ds_read_b128 v[178:181], v239 offset:4096
	ds_read_b128 v[208:211], v239 offset:5120
	ds_read_b128 v[212:215], v239 offset:6144
	ds_read_b128 v[216:219], v239 offset:7168
	global_load_lds_dwordx4 v200, s[86:87]
	s_add_i32 m0, s62, 0xe000
	s_nop 0
	global_load_lds_dwordx4 v202, s[86:87]
	s_waitcnt vmcnt(8)
	s_waitcnt lgkmcnt(0)
	s_barrier
	s_setprio 1
	s_waitcnt lgkmcnt(0)
	v_mfma_f32_16x16x32_bf16 v[6:9], v[10:13], v[66:69], v[6:9]
	v_mfma_f32_16x16x32_bf16 v[6:9], v[14:17], v[70:73], v[6:9]
	v_mfma_f32_16x16x32_bf16 v[2:5], v[42:45], v[66:69], v[2:5]
	v_mfma_f32_16x16x32_bf16 v[2:5], v[46:49], v[70:73], v[2:5]
	v_mfma_f32_16x16x32_bf16 v[158:161], v[10:13], v[170:173], v[158:161]
	v_mfma_f32_16x16x32_bf16 v[158:161], v[14:17], v[174:177], v[158:161]
	v_mfma_f32_16x16x32_bf16 v[154:157], v[42:45], v[170:173], v[154:157]
	v_mfma_f32_16x16x32_bf16 v[154:157], v[46:49], v[174:177], v[154:157]
	v_mfma_f32_16x16x32_bf16 v[142:145], v[10:13], v[178:181], v[142:145]
	v_mfma_f32_16x16x32_bf16 v[142:145], v[14:17], v[208:211], v[142:145]
	v_mfma_f32_16x16x32_bf16 v[138:141], v[42:45], v[178:181], v[138:141]
	v_mfma_f32_16x16x32_bf16 v[138:141], v[46:49], v[208:211], v[138:141]
	v_mfma_f32_16x16x32_bf16 v[126:129], v[10:13], v[212:215], v[126:129]
	v_mfma_f32_16x16x32_bf16 v[126:129], v[14:17], v[216:219], v[126:129]
	v_mfma_f32_16x16x32_bf16 v[122:125], v[42:45], v[212:215], v[122:125]
	v_mfma_f32_16x16x32_bf16 v[122:125], v[46:49], v[216:219], v[122:125]
	s_setprio 0
	s_setprio 1
	v_mfma_f32_16x16x32_bf16 v[166:169], v[50:53], v[66:69], v[166:169]
	v_mfma_f32_16x16x32_bf16 v[166:169], v[54:57], v[70:73], v[166:169]
	v_mfma_f32_16x16x32_bf16 v[66:69], v[58:61], v[66:69], v[162:165]
	v_mfma_f32_16x16x32_bf16 v[66:69], v[62:65], v[70:73], v[66:69]
	v_mfma_f32_16x16x32_bf16 v[146:149], v[58:61], v[170:173], v[146:149]
	v_mfma_f32_16x16x32_bf16 v[146:149], v[62:65], v[174:177], v[146:149]
	v_mfma_f32_16x16x32_bf16 v[134:137], v[50:53], v[178:181], v[134:137]
	v_mfma_f32_16x16x32_bf16 v[134:137], v[54:57], v[208:211], v[134:137]
	v_mfma_f32_16x16x32_bf16 v[130:133], v[58:61], v[178:181], v[130:133]
	v_mfma_f32_16x16x32_bf16 v[130:133], v[62:65], v[208:211], v[130:133]
	v_mfma_f32_16x16x32_bf16 v[118:121], v[50:53], v[212:215], v[118:121]
	v_mfma_f32_16x16x32_bf16 v[118:121], v[54:57], v[216:219], v[118:121]
	v_mfma_f32_16x16x32_bf16 v[114:117], v[58:61], v[212:215], v[114:117]
	v_mfma_f32_16x16x32_bf16 v[114:117], v[62:65], v[216:219], v[114:117]
	v_mfma_f32_16x16x32_bf16 v[70:73], v[50:53], v[170:173], v[150:153]
	v_mfma_f32_16x16x32_bf16 v[70:73], v[54:57], v[174:177], v[70:73]
	s_setprio 0
	s_barrier
	s_add_i32 vcc_lo, s96, s61
	s_mov_b32 m0, vcc_lo
	ds_read_b128 v[150:153], v239 offset:16384
	ds_read_b128 v[162:165], v239 offset:17408
	ds_read_b128 v[170:173], v239 offset:18432
	ds_read_b128 v[174:177], v239 offset:19456
	ds_read_b128 v[178:181], v239 offset:20480
	ds_read_b128 v[208:211], v239 offset:21504
	ds_read_b128 v[212:215], v239 offset:22528
	ds_read_b128 v[216:219], v239 offset:23552
	global_load_lds_dwordx4 v186, s[88:89]
	s_add_i32 m0, vcc_lo, 0x2000
	s_add_u32 vcc_lo, s88, 0x100000
	s_addc_u32 vcc_hi, s89, 0
	s_add_i32 s58, s70, s61
	global_load_lds_dwordx4 v190, s[88:89]
	s_mov_b32 m0, s58
	s_nop 0
	global_load_lds_dwordx4 v186, vcc
	s_add_i32 m0, s58, 0x2000
	s_nop 0
	global_load_lds_dwordx4 v190, vcc
	s_mov_b32 m0, s62
	s_nop 0
	global_load_lds_dwordx4 v184, s[90:91]
	s_mov_b32 m0, s63
	s_nop 0
	global_load_lds_dwordx4 v188, s[90:91]
	s_waitcnt vmcnt(8)
	s_waitcnt lgkmcnt(0)
	s_barrier
	s_setprio 1
	s_waitcnt lgkmcnt(0)
	v_mfma_f32_16x16x32_bf16 v[110:113], v[10:13], v[150:153], v[110:113]
	v_mfma_f32_16x16x32_bf16 v[110:113], v[14:17], v[162:165], v[110:113]
	v_mfma_f32_16x16x32_bf16 v[106:109], v[42:45], v[150:153], v[106:109]
	v_mfma_f32_16x16x32_bf16 v[106:109], v[46:49], v[162:165], v[106:109]
	v_mfma_f32_16x16x32_bf16 v[94:97], v[10:13], v[170:173], v[94:97]
	v_mfma_f32_16x16x32_bf16 v[94:97], v[14:17], v[174:177], v[94:97]
	v_mfma_f32_16x16x32_bf16 v[90:93], v[42:45], v[170:173], v[90:93]
	v_mfma_f32_16x16x32_bf16 v[90:93], v[46:49], v[174:177], v[90:93]
	v_mfma_f32_16x16x32_bf16 v[78:81], v[10:13], v[178:181], v[78:81]
	v_mfma_f32_16x16x32_bf16 v[78:81], v[14:17], v[208:211], v[78:81]
	v_mfma_f32_16x16x32_bf16 v[74:77], v[42:45], v[178:181], v[74:77]
	v_mfma_f32_16x16x32_bf16 v[74:77], v[46:49], v[208:211], v[74:77]
	v_mfma_f32_16x16x32_bf16 v[10:13], v[10:13], v[212:215], v[30:33]
	v_mfma_f32_16x16x32_bf16 v[10:13], v[14:17], v[216:219], v[10:13]
	v_mfma_f32_16x16x32_bf16 v[14:17], v[42:45], v[212:215], v[26:29]
	v_mfma_f32_16x16x32_bf16 v[14:17], v[46:49], v[216:219], v[14:17]
	s_setprio 0
	s_setprio 1
	v_mfma_f32_16x16x32_bf16 v[26:29], v[50:53], v[150:153], v[102:105]
	v_mfma_f32_16x16x32_bf16 v[42:45], v[54:57], v[162:165], v[26:29]
	v_mfma_f32_16x16x32_bf16 v[26:29], v[58:61], v[150:153], v[98:101]
	v_mfma_f32_16x16x32_bf16 v[46:49], v[62:65], v[162:165], v[26:29]
	v_mfma_f32_16x16x32_bf16 v[26:29], v[50:53], v[170:173], v[86:89]
	v_mfma_f32_16x16x32_bf16 v[86:89], v[54:57], v[174:177], v[26:29]
	v_mfma_f32_16x16x32_bf16 v[26:29], v[58:61], v[170:173], v[82:85]
	v_mfma_f32_16x16x32_bf16 v[82:85], v[62:65], v[174:177], v[26:29]
	v_mfma_f32_16x16x32_bf16 v[26:29], v[50:53], v[178:181], v[38:41]
	v_mfma_f32_16x16x32_bf16 v[38:41], v[54:57], v[208:211], v[26:29]
	v_mfma_f32_16x16x32_bf16 v[26:29], v[58:61], v[178:181], v[34:37]
	v_mfma_f32_16x16x32_bf16 v[34:37], v[62:65], v[208:211], v[26:29]
	v_mfma_f32_16x16x32_bf16 v[22:25], v[50:53], v[212:215], v[22:25]
	v_mfma_f32_16x16x32_bf16 v[22:25], v[54:57], v[216:219], v[22:25]
	v_mfma_f32_16x16x32_bf16 v[18:21], v[58:61], v[212:215], v[18:21]
	v_mfma_f32_16x16x32_bf16 v[18:21], v[62:65], v[216:219], v[18:21]
	s_setprio 0
	s_barrier
; #define PG8_STAGE(bufoff, gbase, voff) do { _Pragma("unroll") for (int _i = 0; _i < 2; ++_i) \
;         __builtin_amdgcn_global_load_lds((const unsigned*)((const char*)(gbase) + (voff)[_i]), (PG8_LAS unsigned*)(lds + (bufoff) + ldsw + _i * 8192), 16, 0, 0); } while (0)
; #define PG8_LDA(dst, b, h) do { _Pragma("unroll") for (int m = 0; m < 4; ++m) _Pragma("unroll") for (int k = 0; k < 2; ++k) dst[m][k] = *(const PG8_LAS bf16x8*)(lds + PG8_SA(b, h) + aoff + m * 2048 + k * 1024); } while (0)
; #define PG8_LDB(dst, b, h) do { _Pragma("unroll") for (int n = 0; n < 2; ++n) _Pragma("unroll") for (int k = 0; k < 2; ++k) dst[n][k] = *(const PG8_LAS bf16x8*)(lds + PG8_SB(b, h) + boff + n * 2048 + k * 1024); } while (0)
; #define PG8_MMA(ai, bj, At, Bt) do { __builtin_amdgcn_s_setprio(1); _Pragma("unroll") for (int m = 0; m < 4; ++m) _Pragma("unroll") for (int n = 0; n < 2; ++n) _Pragma("unroll") for (int k = 0; k < 2; ++k) \
;         acc[ai][bj][m][n] = __builtin_amdgcn_mfma_f32_16x16x32_bf16(Bt[n][k], At[m][k], acc[ai][bj][m][n], 0, 0, 0); __builtin_amdgcn_s_setprio(0); } while (0)
; #define PG8_WAIT_V(n) asm volatile("s_waitcnt vmcnt(" #n ")" ::: "memory")
; #define PG8_WAIT_L(n) asm volatile("s_waitcnt lgkmcnt(" #n ")" ::: "memory")
; #define PG8_BAR __builtin_amdgcn_s_barrier()
; #define PG8_SCHED __builtin_amdgcn_sched_barrier(0)
; template <class Epi, class Sched, bool ALIGN_EPI = false, bool SP2 = false>
; __device__ __forceinline__ void gemm_phase(PG8_LAS unsigned char* lds, const Gemm g, const Sched& S, const Epi& E) {
;     ...
;             PG8_LDB(B0, 1, 0); PG8_LDB(B1, 1, 1); PG8_SCHED; PG8_LDA(At, 1, 0); PG8_STAGE(PG8_SA(0, 1), a2 + hstep, voffA);
;             PG8_WAIT_V(8); PG8_WAIT_L(0); PG8_BAR; PG8_MMA(0, 0, At, B0); PG8_MMA(0, 1, At, B1); PG8_BAR; PG8_SCHED;
;             PG8_LDA(At, 1, 1); PG8_STAGE(PG8_SB(1, 0), b3, voffB); PG8_STAGE(PG8_SB(1, 1), b3 + hstep, voffB); PG8_STAGE(PG8_SA(1, 0), a3, voffA);
;             PG8_WAIT_V(8); PG8_WAIT_L(0); PG8_BAR; PG8_MMA(1, 0, At, B0); PG8_MMA(1, 1, At, B1); PG8_BAR; PG8_SCHED;
	s_add_i32 s58, 0, 0x18000
	s_add_i32 s59, 0, 0x1c000
	v_add_u32_e32 v54, s58, v1
	v_add_u32_e32 v98, s59, v1
	ds_read_b128 v[26:29], v54
	ds_read_b128 v[30:33], v54 offset:1024
	ds_read_b128 v[50:53], v54 offset:2048
	ds_read_b128 v[54:57], v54 offset:3072
	ds_read_b128 v[58:61], v98
	ds_read_b128 v[62:65], v98 offset:1024
	ds_read_b128 v[170:173], v98 offset:2048
	ds_read_b128 v[174:177], v98 offset:3072
	s_add_u32 s90, s90, 0x100000
	s_addc_u32 s91, s91, 0
	s_mov_b32 m0, s73
	ds_read_b128 v[98:101], v239 offset:32768
	ds_read_b128 v[102:105], v239 offset:33792
	ds_read_b128 v[178:181], v239 offset:34816
	ds_read_b128 v[208:211], v239 offset:35840
	ds_read_b128 v[212:215], v239 offset:36864
	ds_read_b128 v[216:219], v239 offset:37888
	ds_read_b128 v[220:223], v239 offset:38912
	ds_read_b128 v[224:227], v239 offset:39936
	global_load_lds_dwordx4 v184, s[90:91]
	s_mov_b32 m0, s75
	s_nop 0
	global_load_lds_dwordx4 v188, s[90:91]
	s_waitcnt vmcnt(8)
	s_waitcnt lgkmcnt(0)
	s_barrier
	s_setprio 1
	s_waitcnt lgkmcnt(0)
	v_mfma_f32_16x16x32_bf16 v[150:153], v[26:29], v[178:181], v[158:161]
	v_mfma_f32_16x16x32_bf16 v[158:161], v[30:33], v[208:211], v[150:153]
	v_mfma_f32_16x16x32_bf16 v[6:9], v[26:29], v[98:101], v[6:9]
	v_mfma_f32_16x16x32_bf16 v[6:9], v[30:33], v[102:105], v[6:9]
	v_mfma_f32_16x16x32_bf16 v[2:5], v[50:53], v[98:101], v[2:5]
	v_mfma_f32_16x16x32_bf16 v[2:5], v[54:57], v[102:105], v[2:5]
	v_mfma_f32_16x16x32_bf16 v[150:153], v[50:53], v[178:181], v[154:157]
	v_mfma_f32_16x16x32_bf16 v[154:157], v[54:57], v[208:211], v[150:153]
	v_mfma_f32_16x16x32_bf16 v[142:145], v[26:29], v[212:215], v[142:145]
	v_mfma_f32_16x16x32_bf16 v[142:145], v[30:33], v[216:219], v[142:145]
	v_mfma_f32_16x16x32_bf16 v[138:141], v[50:53], v[212:215], v[138:141]
	v_mfma_f32_16x16x32_bf16 v[138:141], v[54:57], v[216:219], v[138:141]
	v_mfma_f32_16x16x32_bf16 v[126:129], v[26:29], v[220:223], v[126:129]
	v_mfma_f32_16x16x32_bf16 v[126:129], v[30:33], v[224:227], v[126:129]
	v_mfma_f32_16x16x32_bf16 v[122:125], v[50:53], v[220:223], v[122:125]
	v_mfma_f32_16x16x32_bf16 v[122:125], v[54:57], v[224:227], v[122:125]
	s_setprio 0
	s_setprio 1
	v_mfma_f32_16x16x32_bf16 v[66:69], v[170:173], v[98:101], v[66:69]
	v_mfma_f32_16x16x32_bf16 v[162:165], v[174:177], v[102:105], v[66:69]
	v_mfma_f32_16x16x32_bf16 v[150:153], v[58:61], v[98:101], v[166:169]
	v_mfma_f32_16x16x32_bf16 v[166:169], v[62:65], v[102:105], v[150:153]
	v_mfma_f32_16x16x32_bf16 v[66:69], v[58:61], v[178:181], v[70:73]
	v_mfma_f32_16x16x32_bf16 v[150:153], v[62:65], v[208:211], v[66:69]
	v_mfma_f32_16x16x32_bf16 v[66:69], v[170:173], v[178:181], v[146:149]
	v_mfma_f32_16x16x32_bf16 v[146:149], v[174:177], v[208:211], v[66:69]
	v_mfma_f32_16x16x32_bf16 v[66:69], v[58:61], v[212:215], v[134:137]
	v_mfma_f32_16x16x32_bf16 v[134:137], v[62:65], v[216:219], v[66:69]
	v_mfma_f32_16x16x32_bf16 v[66:69], v[170:173], v[212:215], v[130:133]
	v_mfma_f32_16x16x32_bf16 v[130:133], v[174:177], v[216:219], v[66:69]
	v_mfma_f32_16x16x32_bf16 v[66:69], v[58:61], v[220:223], v[118:121]
	v_mfma_f32_16x16x32_bf16 v[118:121], v[62:65], v[224:227], v[66:69]
	v_mfma_f32_16x16x32_bf16 v[66:69], v[170:173], v[220:223], v[114:117]
	v_mfma_f32_16x16x32_bf16 v[114:117], v[174:177], v[224:227], v[66:69]
	s_setprio 0
	s_barrier
	s_add_i32 s58, s58, s61
	s_add_u32 s100, s88, 0x80
	s_addc_u32 s101, s89, 0
	s_mov_b32 m0, s58
	s_nop 1
	ds_read_b128 v[66:69], v239 offset:49152
	ds_read_b128 v[70:73], v239 offset:50176
	ds_read_b128 v[178:181], v239 offset:51200
	ds_read_b128 v[208:211], v239 offset:52224
	ds_read_b128 v[212:215], v239 offset:53248
	ds_read_b128 v[216:219], v239 offset:54272
	ds_read_b128 v[220:223], v239 offset:55296
	ds_read_b128 v[224:227], v239 offset:56320
	global_load_lds_dwordx4 v186, s[100:101]
	s_add_i32 m0, s58, 0x2000
	s_add_i32 s58, s59, s61
	global_load_lds_dwordx4 v190, s[100:101]
	s_add_u32 s88, s88, 0x100080
	s_addc_u32 s89, s89, 0
	s_add_u32 s100, s90, 0xfff00080
	s_addc_u32 s101, s91, -1
	s_mov_b32 m0, s58
	s_nop 0
	global_load_lds_dwordx4 v186, s[88:89]
	s_add_i32 m0, s58, 0x2000
	s_nop 0
	global_load_lds_dwordx4 v190, s[88:89]
	s_mov_b32 m0, s29
	s_nop 0
	global_load_lds_dwordx4 v184, s[100:101]
	s_mov_b32 m0, s95
	s_nop 0
	global_load_lds_dwordx4 v188, s[100:101]
	s_waitcnt vmcnt(8)
	s_waitcnt lgkmcnt(0)
	s_barrier
	s_setprio 1
	s_waitcnt lgkmcnt(0)
	v_mfma_f32_16x16x32_bf16 v[98:101], v[26:29], v[66:69], v[110:113]
	v_mfma_f32_16x16x32_bf16 v[110:113], v[30:33], v[70:73], v[98:101]
	v_mfma_f32_16x16x32_bf16 v[94:97], v[26:29], v[178:181], v[94:97]
	v_mfma_f32_16x16x32_bf16 v[94:97], v[30:33], v[208:211], v[94:97]
	v_mfma_f32_16x16x32_bf16 v[78:81], v[26:29], v[212:215], v[78:81]
	v_mfma_f32_16x16x32_bf16 v[78:81], v[30:33], v[216:219], v[78:81]
	v_mfma_f32_16x16x32_bf16 v[10:13], v[26:29], v[220:223], v[10:13]
	v_mfma_f32_16x16x32_bf16 v[30:33], v[30:33], v[224:227], v[10:13]
	v_mfma_f32_16x16x32_bf16 v[98:101], v[50:53], v[66:69], v[106:109]
	v_mfma_f32_16x16x32_bf16 v[106:109], v[54:57], v[70:73], v[98:101]
	v_mfma_f32_16x16x32_bf16 v[90:93], v[50:53], v[178:181], v[90:93]
	v_mfma_f32_16x16x32_bf16 v[90:93], v[54:57], v[208:211], v[90:93]
	v_mfma_f32_16x16x32_bf16 v[74:77], v[50:53], v[212:215], v[74:77]
	v_mfma_f32_16x16x32_bf16 v[74:77], v[54:57], v[216:219], v[74:77]
	v_mfma_f32_16x16x32_bf16 v[10:13], v[50:53], v[220:223], v[14:17]
	v_mfma_f32_16x16x32_bf16 v[26:29], v[54:57], v[224:227], v[10:13]
	s_setprio 0
	s_setprio 1
	v_mfma_f32_16x16x32_bf16 v[10:13], v[58:61], v[66:69], v[42:45]
	v_mfma_f32_16x16x32_bf16 v[102:105], v[62:65], v[70:73], v[10:13]
	v_mfma_f32_16x16x32_bf16 v[10:13], v[170:173], v[66:69], v[46:49]
	v_mfma_f32_16x16x32_bf16 v[98:101], v[174:177], v[70:73], v[10:13]
	v_mfma_f32_16x16x32_bf16 v[10:13], v[58:61], v[178:181], v[86:89]
	v_mfma_f32_16x16x32_bf16 v[86:89], v[62:65], v[208:211], v[10:13]
	v_mfma_f32_16x16x32_bf16 v[10:13], v[170:173], v[178:181], v[82:85]
	v_mfma_f32_16x16x32_bf16 v[82:85], v[174:177], v[208:211], v[10:13]
	v_mfma_f32_16x16x32_bf16 v[10:13], v[58:61], v[212:215], v[38:41]
	v_mfma_f32_16x16x32_bf16 v[38:41], v[62:65], v[216:219], v[10:13]
	v_mfma_f32_16x16x32_bf16 v[10:13], v[170:173], v[212:215], v[34:37]
	v_mfma_f32_16x16x32_bf16 v[34:37], v[174:177], v[216:219], v[10:13]
	v_mfma_f32_16x16x32_bf16 v[10:13], v[58:61], v[220:223], v[22:25]
	v_mfma_f32_16x16x32_bf16 v[22:25], v[62:65], v[224:227], v[10:13]
	v_mfma_f32_16x16x32_bf16 v[10:13], v[170:173], v[220:223], v[18:21]
	v_mfma_f32_16x16x32_bf16 v[18:21], v[174:177], v[224:227], v[10:13]
	s_setprio 0
	s_barrier
	s_add_i32 s93, s93, 2
	s_add_u32 s86, s86, 0x100
	s_addc_u32 s87, s87, 0
	s_add_u32 s85, s85, 0x100
	s_addc_u32 s92, s92, 0
	s_cmp_gt_u32 s93, 61
	s_cbranch_scc0 .LBB0_2650
	s_and_b64 vcc, exec, s[42:43]
	s_cbranch_vccz .LBB0_2653
	s_barrier
